# baseline (speedup 1.0000x reference)
.LBB0_176:
	s_sleep 8
	global_load_dword v2, v0, s[4:5] offset:32 sc1
	s_waitcnt vmcnt(0)
	v_and_b32_e32 v2, 0xffff0000, v2
	v_cmp_ne_u32_e32 vcc, v2, v1
	s_or_b64 s[6:7], vcc, s[6:7]
	s_andn2_b64 exec, exec, s[6:7]
	s_cbranch_execnz .LBB0_176
